# speedup vs baseline: 1.0122x; 1.0018x over previous
; #define MFMA32(a, b, c) __builtin_amdgcn_mfma_f32_32x32x16_bf16((a), (b), (c), 0, 0, 0)
; DI f32x16 zero16() { f32x16 z; _Pragma("unroll") for (int i = 0; i < 16; ++i) z[i] = 0.f; return z; }
; DI void attn_item(const Params& P, int half, int item, char* smem) {
;     ...
;   for (int kt = 0; kt < nkt; ++kt) {
;     asm volatile("s_waitcnt vmcnt(5) lgkmcnt(0)" ::: "memory");
;     __builtin_amdgcn_s_barrier();
;     {
;       const int nxt = (cur == 0) ? 2 : cur - 1;
;       attn_dma_k(P, head, tkb + (kt + 2) * 64, smem, nxt, w, lane);
;       attn_dma_v(P, head, tkb + (kt + 2) * 64, smem, nxt, w, lane);
;     }
;     const char* kn = smem + cur * 40960;
;     const char* kr = kn + 16384;
;     f32x16 st[2]; st[0] = zero16(); st[1] = zero16();
;     _Pragma("unroll") for (int s = 0; s < 8; ++s) {
;       const int po = ((2 * s + h) ^ rn) << 4;
;       bf16x8 a0 = *(const bf16x8*)(kn + r * 256 + po);
;       bf16x8 a1 = *(const bf16x8*)(kn + (32 + r) * 256 + po);
;       st[0] = MFMA32(a0, qf[s], st[0]);
;       st[1] = MFMA32(a1, qf[s], st[1]);
;     }
;     _Pragma("unroll") for (int s = 0; s < 4; ++s) {
;       const int po = ((2 * s + h) ^ rr8) << 4;
;       bf16x8 a0 = *(const bf16x8*)(kr + r * 128 + po);
;       bf16x8 a1 = *(const bf16x8*)(kr + (32 + r) * 128 + po);
;       st[0] = MFMA32(a0, qf[8 + s], st[0]);
;       st[1] = MFMA32(a1, qf[8 + s], st[1]);
;     }
.LBB0_729:
	s_mul_i32 s16, s13, 0xa000
	s_add_i32 s1, s16, 0xffff6000
	s_cmp_lg_u32 s13, 0
	s_cselect_b32 s1, s1, 0x14000
	v_mov_b32_e32 v197, v64
	s_add_u32 s80, s1, s82
	s_add_u32 s81, s80, 0x2000
	s_add_u32 s83, s80, 0x4000
	s_add_u32 s90, s80, 0x6000
	s_add_u32 s91, s80, 0x8000
	s_lshl_b32 s84, s0, 11
	s_mov_b32 s85, 0
	s_lshl_b32 s86, s0, 7
	s_mov_b32 s87, 0
	s_ashr_i32 s1, s0, 31
	s_lshl_b64 s[14:15], s[0:1], 1
	s_mov_b32 s1, s16
	v_add_u32_e32 v152, s1, v173
	s_waitcnt vmcnt(5) lgkmcnt(0)
	s_barrier
	v_add_u32_e32 v68, v152, v175
	ds_read_b128 v[64:67], v68
	ds_read_b128 v[68:71], v68 offset:8192
	v_add_u32_e32 v195, v152, v176
	ds_read_b128 v[206:209], v195
	ds_read_b128 v[210:213], v195 offset:8192
	v_add_u32_e32 v195, v152, v177
	ds_read_b128 v[214:217], v195
	ds_read_b128 v[252:255], v195 offset:8192
	v_add_u32_e32 v205, s1, v174
	v_cmp_lt_i32_e32 vcc, v199, v198
	s_add_i32 s1, s13, 1
	s_cmp_lg_u32 s13, 2
	s_cselect_b32 s13, s1, 0
	s_add_i32 s12, s12, -1
	s_add_i32 s0, s0, 64
	s_cmp_lg_u32 s12, 0
	s_waitcnt lgkmcnt(4)
	v_mfma_f32_32x32x16_bf16 v[80:95], v[64:67], v[96:99], 0
	v_mfma_f32_32x32x16_bf16 v[64:79], v[68:71], v[96:99], 0
	s_waitcnt lgkmcnt(2)
	v_mfma_f32_32x32x16_bf16 v[80:95], v[206:209], v[100:103], v[80:95]
	v_mfma_f32_32x32x16_bf16 v[64:79], v[210:213], v[100:103], v[64:79]
	v_add_u32_e32 v195, v152, v178
	ds_read_b128 v[206:209], v195
	ds_read_b128 v[210:213], v195 offset:8192
	s_mov_b32 m0, s80
	v_lshl_add_u64 v[168:169], v[156:157], 0, s[84:85]
	global_load_lds_dwordx4 v[168:169], off
	s_waitcnt lgkmcnt(2)
	v_mfma_f32_32x32x16_bf16 v[80:95], v[214:217], v[104:107], v[80:95]
	v_mfma_f32_32x32x16_bf16 v[64:79], v[252:255], v[104:107], v[64:79]
	v_add_u32_e32 v195, v152, v179
	ds_read_b128 v[214:217], v195
	ds_read_b128 v[252:255], v195 offset:8192
	s_waitcnt lgkmcnt(2)
	v_mfma_f32_32x32x16_bf16 v[80:95], v[206:209], v[108:111], v[80:95]
	v_mfma_f32_32x32x16_bf16 v[64:79], v[210:213], v[108:111], v[64:79]
	v_add_u32_e32 v195, v152, v180
	ds_read_b128 v[206:209], v195
	ds_read_b128 v[210:213], v195 offset:8192
	s_mov_b32 m0, s81
	v_lshl_add_u64 v[170:171], v[158:159], 0, s[84:85]
	global_load_lds_dwordx4 v[170:171], off
	s_waitcnt lgkmcnt(2)
	v_mfma_f32_32x32x16_bf16 v[80:95], v[214:217], v[112:115], v[80:95]
	v_mfma_f32_32x32x16_bf16 v[64:79], v[252:255], v[112:115], v[64:79]
	v_add_u32_e32 v195, v152, v181
	ds_read_b128 v[214:217], v195
	ds_read_b128 v[252:255], v195 offset:8192
	s_waitcnt lgkmcnt(2)
	v_mfma_f32_32x32x16_bf16 v[80:95], v[206:209], v[116:119], v[80:95]
	v_mfma_f32_32x32x16_bf16 v[64:79], v[210:213], v[116:119], v[64:79]
	v_add_u32_e32 v195, v152, v182
	ds_read_b128 v[206:209], v195
	ds_read_b128 v[210:213], v195 offset:8192
	s_mov_b32 m0, s83
	v_lshl_add_u64 v[168:169], v[160:161], 0, s[86:87]
	global_load_lds_dwordx4 v[168:169], off
	s_waitcnt lgkmcnt(2)
	v_mfma_f32_32x32x16_bf16 v[80:95], v[214:217], v[120:123], v[80:95]
	v_mfma_f32_32x32x16_bf16 v[64:79], v[252:255], v[120:123], v[64:79]
	v_add_u32_e32 v195, v205, v183
	ds_read_b128 v[214:217], v195 offset:16384
	ds_read_b128 v[252:255], v195 offset:20480
	s_waitcnt lgkmcnt(2)
	v_mfma_f32_32x32x16_bf16 v[80:95], v[206:209], v[124:127], v[80:95]
	v_mfma_f32_32x32x16_bf16 v[64:79], v[210:213], v[124:127], v[64:79]
	v_add_u32_e32 v195, v205, v184
	ds_read_b128 v[206:209], v195 offset:16384
	ds_read_b128 v[210:213], v195 offset:20480
	s_mov_b32 m0, s90
	v_lshl_add_u64 v[170:171], v[162:163], 0, s[14:15]
	global_load_lds_dwordx4 v[170:171], off
	s_waitcnt lgkmcnt(2)
	v_mfma_f32_32x32x16_bf16 v[80:95], v[214:217], v[128:131], v[80:95]
	v_mfma_f32_32x32x16_bf16 v[64:79], v[252:255], v[128:131], v[64:79]
	v_add_u32_e32 v195, v205, v185
	ds_read_b128 v[214:217], v195 offset:16384
	ds_read_b128 v[252:255], v195 offset:20480
	s_waitcnt lgkmcnt(2)
	v_mfma_f32_32x32x16_bf16 v[80:95], v[206:209], v[132:135], v[80:95]
	v_mfma_f32_32x32x16_bf16 v[64:79], v[210:213], v[132:135], v[64:79]
	v_add_u32_e32 v195, v205, v186
	ds_read_b128 v[206:209], v195 offset:16384
	ds_read_b128 v[210:213], v195 offset:20480
	s_mov_b32 m0, s91
	v_lshl_add_u64 v[168:169], v[164:165], 0, s[14:15]
	global_load_lds_dwordx4 v[168:169], off
	v_add_u32_e32 v205, v205, v167
	s_waitcnt lgkmcnt(2)
	v_mfma_f32_32x32x16_bf16 v[80:95], v[214:217], v[136:139], v[80:95]
	v_mfma_f32_32x32x16_bf16 v[64:79], v[252:255], v[136:139], v[64:79]
	s_waitcnt lgkmcnt(0)
; DI void attn_item(const Params& P, int half, int item, char* smem) {
;     ...
;     float mx = st[0][0];
;     _Pragma("unroll") for (int i = 0; i < 16; ++i) { mx = fmaxf(mx, st[0][i]); mx = fmaxf(mx, st[1][i]); }
;     mx = fmaxf(mx, __shfl_xor(mx, 32));
;     const float mnew = fmaxf(mrun, mx);
;     const float alpha = __builtin_amdgcn_exp2f(mrun - mnew);
;     mrun = mnew;
;     float psum = 0.f;
;     _Pragma("unroll") for (int i = 0; i < 16; ++i) {
;       st[0][i] = __builtin_amdgcn_exp2f(st[0][i] - mnew); psum += st[0][i];
;       st[1][i] = __builtin_amdgcn_exp2f(st[1][i] - mnew); psum += st[1][i];
;     }
;     lrun = lrun * alpha + psum;
;     _Pragma("unroll") for (int mt = 0; mt < 4; ++mt) {
;       _Pragma("unroll") for (int i = 0; i < 16; ++i) o[mt][i] *= alpha;
	v_mfma_f32_32x32x16_bf16 v[80:95], v[206:209], v[140:143], v[80:95]
	v_mfma_f32_32x32x16_bf16 v[64:79], v[210:213], v[140:143], v[64:79]
	s_nop 10
	v_max_f32_e32 v195, v80, v80
	v_max_f32_e32 v152, v64, v64
	v_max_f32_e32 v152, v195, v152
	v_max3_f32 v152, v152, v81, v65
	v_max3_f32 v152, v152, v82, v66
	v_max3_f32 v152, v152, v83, v67
	v_max3_f32 v152, v152, v84, v68
	v_max3_f32 v152, v152, v85, v69
	v_max3_f32 v152, v152, v86, v70
	v_max3_f32 v152, v152, v87, v71
	v_max3_f32 v152, v152, v88, v72
	v_max3_f32 v152, v152, v89, v73
	v_max3_f32 v152, v152, v90, v74
	v_max3_f32 v152, v152, v91, v75
	v_max3_f32 v152, v152, v92, v76
	v_max3_f32 v152, v152, v93, v77
	v_max3_f32 v152, v152, v94, v78
	v_max3_f32 v195, v152, v95, v79
	v_cndmask_b32_e32 v152, v145, v199, vcc
	v_lshlrev_b32_e32 v152, 2, v152
	v_mov_b32_e32 v206, v195
	s_nop 1
	v_permlane32_swap_b32_e32 v206, v195
	v_max3_f32 v195, v196, v195, v206
	v_sub_f32_e32 v64, v64, v195
	v_exp_f32_e32 v206, v64
	v_sub_f32_e32 v64, v81, v195
	v_exp_f32_e32 v81, v64
	v_sub_f32_e32 v64, v65, v195
	v_exp_f32_e32 v65, v64
	v_sub_f32_e32 v64, v82, v195
	v_exp_f32_e32 v82, v64
	v_sub_f32_e32 v64, v66, v195
	v_exp_f32_e32 v207, v64
	v_sub_f32_e32 v64, v83, v195
	v_exp_f32_e32 v83, v64
	v_sub_f32_e32 v64, v67, v195
	v_exp_f32_e32 v208, v64
	v_sub_f32_e32 v64, v84, v195
	v_exp_f32_e32 v84, v64
	v_sub_f32_e32 v64, v68, v195
	v_exp_f32_e32 v209, v64
	v_sub_f32_e32 v64, v85, v195
	v_exp_f32_e32 v68, v64
	v_sub_f32_e32 v64, v69, v195
	v_exp_f32_e32 v85, v64
	v_sub_f32_e32 v64, v86, v195
	v_exp_f32_e32 v69, v64
	v_sub_f32_e32 v64, v70, v195
	v_exp_f32_e32 v86, v64
	v_sub_f32_e32 v64, v87, v195
	v_exp_f32_e32 v70, v64
	v_sub_f32_e32 v64, v71, v195
	v_exp_f32_e32 v87, v64
	v_sub_f32_e32 v64, v88, v195
	v_exp_f32_e32 v88, v64
	v_sub_f32_e32 v64, v72, v195
	v_exp_f32_e32 v210, v64
	v_sub_f32_e32 v64, v89, v195
	v_exp_f32_e32 v89, v64
	v_sub_f32_e32 v64, v73, v195
	v_exp_f32_e32 v211, v64
	v_sub_f32_e32 v64, v90, v195
	v_exp_f32_e32 v90, v64
	v_sub_f32_e32 v64, v74, v195
	v_exp_f32_e32 v212, v64
	v_sub_f32_e32 v64, v91, v195
	v_exp_f32_e32 v91, v64
	v_sub_f32_e32 v64, v75, v195
	v_exp_f32_e32 v213, v64
	v_sub_f32_e32 v64, v92, v195
	v_exp_f32_e32 v92, v64
	v_sub_f32_e32 v64, v76, v195
	v_exp_f32_e32 v214, v64
	v_sub_f32_e32 v64, v93, v195
	v_sub_f32_e32 v80, v80, v195
	v_exp_f32_e32 v93, v64
	v_sub_f32_e32 v64, v77, v195
	v_exp_f32_e32 v80, v80
	v_exp_f32_e32 v215, v64
	v_sub_f32_e32 v64, v94, v195
	v_exp_f32_e32 v94, v64
	v_sub_f32_e32 v64, v78, v195
	v_exp_f32_e32 v216, v64
	v_sub_f32_e32 v64, v95, v195
	v_exp_f32_e32 v95, v64
	v_sub_f32_e32 v64, v79, v195
	v_exp_f32_e32 v217, v64
	v_sub_f32_e32 v196, v196, v195
	v_exp_f32_e32 v196, v196
	v_add_f32_e32 v64, 0, v80
	v_add_f32_e32 v64, v206, v64
	v_add_f32_e32 v64, v81, v64
	v_cmp_neq_f32_e32 vcc, 1.0, v196
	s_cbranch_vccz .Lattn_norescale
	v_pk_mul_f32 v[0:1], v[0:1], v[196:197] op_sel_hi:[1,0]
	v_pk_mul_f32 v[2:3], v[2:3], v[196:197] op_sel_hi:[1,0]
	v_pk_mul_f32 v[4:5], v[4:5], v[196:197] op_sel_hi:[1,0]
	v_pk_mul_f32 v[6:7], v[6:7], v[196:197] op_sel_hi:[1,0]
	v_pk_mul_f32 v[8:9], v[8:9], v[196:197] op_sel_hi:[1,0]
	v_pk_mul_f32 v[10:11], v[10:11], v[196:197] op_sel_hi:[1,0]
	v_pk_mul_f32 v[12:13], v[12:13], v[196:197] op_sel_hi:[1,0]
	v_pk_mul_f32 v[14:15], v[14:15], v[196:197] op_sel_hi:[1,0]
	v_pk_mul_f32 v[16:17], v[16:17], v[196:197] op_sel_hi:[1,0]
	v_pk_mul_f32 v[18:19], v[18:19], v[196:197] op_sel_hi:[1,0]
	v_pk_mul_f32 v[20:21], v[20:21], v[196:197] op_sel_hi:[1,0]
	v_pk_mul_f32 v[22:23], v[22:23], v[196:197] op_sel_hi:[1,0]
	v_pk_mul_f32 v[24:25], v[24:25], v[196:197] op_sel_hi:[1,0]
	v_pk_mul_f32 v[26:27], v[26:27], v[196:197] op_sel_hi:[1,0]
	v_pk_mul_f32 v[28:29], v[28:29], v[196:197] op_sel_hi:[1,0]
	v_pk_mul_f32 v[30:31], v[30:31], v[196:197] op_sel_hi:[1,0]
	v_pk_mul_f32 v[32:33], v[32:33], v[196:197] op_sel_hi:[1,0]
	v_pk_mul_f32 v[34:35], v[34:35], v[196:197] op_sel_hi:[1,0]
	v_pk_mul_f32 v[36:37], v[36:37], v[196:197] op_sel_hi:[1,0]
	v_pk_mul_f32 v[38:39], v[38:39], v[196:197] op_sel_hi:[1,0]
	v_pk_mul_f32 v[40:41], v[40:41], v[196:197] op_sel_hi:[1,0]
	v_pk_mul_f32 v[42:43], v[42:43], v[196:197] op_sel_hi:[1,0]
	v_pk_mul_f32 v[44:45], v[44:45], v[196:197] op_sel_hi:[1,0]
	v_pk_mul_f32 v[46:47], v[46:47], v[196:197] op_sel_hi:[1,0]
	v_pk_mul_f32 v[48:49], v[48:49], v[196:197] op_sel_hi:[1,0]
	v_pk_mul_f32 v[50:51], v[50:51], v[196:197] op_sel_hi:[1,0]
	v_pk_mul_f32 v[52:53], v[52:53], v[196:197] op_sel_hi:[1,0]
	v_pk_mul_f32 v[54:55], v[54:55], v[196:197] op_sel_hi:[1,0]
	v_pk_mul_f32 v[56:57], v[56:57], v[196:197] op_sel_hi:[1,0]
	v_pk_mul_f32 v[58:59], v[58:59], v[196:197] op_sel_hi:[1,0]
	v_pk_mul_f32 v[60:61], v[60:61], v[196:197] op_sel_hi:[1,0]
	v_pk_mul_f32 v[62:63], v[62:63], v[196:197] op_sel_hi:[1,0]

; #define MFMA32(a, b, c) __builtin_amdgcn_mfma_f32_32x32x16_bf16((a), (b), (c), 0, 0, 0)
; DI void gemm_mainloop(const bf16_t* __restrict__ A, int lda, const bf16_t* __restrict__ B, int ldb, int K,
;                       f32x16 (&acc)[2][4], char* smem, const int tid) {
;     ...
;   for (int kt = 0; kt < nk; ++kt) {
;     asm volatile("s_waitcnt vmcnt(8) lgkmcnt(0)" ::: "memory");
;     __builtin_amdgcn_s_barrier();
;     dma_stage(A, lda, B, ldb, (kt + 3) * 32, smem + ((kt + 3) & 3) * STG, w, lane);
;     const char* st = smem + (kt & 3) * STG;
;     _Pragma("unroll") for (int ks = 0; ks < 2; ++ks) {
;       const int oo = ks ? o1 : o0;
;       bf16x8 a0 = *(const bf16x8*)(st + aoff + oo);
;       bf16x8 a1 = *(const bf16x8*)(st + aoff + 32 * 64 + oo);
;       bf16x8 b0 = *(const bf16x8*)(st + boff + oo);
;       bf16x8 b1 = *(const bf16x8*)(st + boff + 32 * 64 + oo);
;       bf16x8 b2 = *(const bf16x8*)(st + boff + 64 * 64 + oo);
;       bf16x8 b3 = *(const bf16x8*)(st + boff + 96 * 64 + oo);
;       acc[0][0] = MFMA32(a0, b0, acc[0][0]); acc[0][1] = MFMA32(a0, b1, acc[0][1]);
;       acc[0][2] = MFMA32(a0, b2, acc[0][2]); acc[0][3] = MFMA32(a0, b3, acc[0][3]);
;       acc[1][0] = MFMA32(a1, b0, acc[1][0]); acc[1][1] = MFMA32(a1, b1, acc[1][1]);
;       acc[1][2] = MFMA32(a1, b2, acc[1][2]); acc[1][3] = MFMA32(a1, b3, acc[1][3]);
;     }
.LBB0_867:
	s_add_i32 s11, s9, 0x18000
	s_and_b32 s11, s11, 0x18000
	v_add_u32_e32 v152, s11, v192
	v_add_u32_e32 v140, v152, v193
	v_lshl_add_u64 v[136:137], v[130:131], 0, s[12:13]
	v_readfirstlane_b32 s11, v140
	v_lshl_add_u64 v[138:139], v[136:137], 0, s[20:21]
	s_mov_b32 m0, s11
	v_add_u32_e32 v142, v152, v194
	s_waitcnt vmcnt(8) lgkmcnt(0)
	s_barrier
	global_load_lds_dwordx4 v[138:139], off
	v_lshl_add_u64 v[138:139], v[128:129], 0, s[12:13]
	v_readfirstlane_b32 s11, v142
	v_add_u32_e32 v161, v152, v195
	v_lshl_add_u64 v[140:141], v[138:139], 0, s[20:21]
	s_mov_b32 m0, s11
	v_lshl_add_u64 v[142:143], v[134:135], 0, s[12:13]
	v_readfirstlane_b32 s11, v161
	v_add_u32_e32 v152, v152, v196
	global_load_lds_dwordx4 v[140:141], off
	v_lshl_add_u64 v[140:141], v[142:143], 0, s[20:21]
	s_mov_b32 m0, s11
	v_readfirstlane_b32 s11, v152
	global_load_lds_dwordx4 v[140:141], off
	s_mov_b32 m0, s11
	s_and_b32 s11, s9, 0x10000
	v_lshl_add_u64 v[140:141], v[132:133], 0, s[12:13]
	s_add_i32 s18, s11, 0
	v_lshl_add_u64 v[162:163], v[140:141], 0, s[20:21]
	v_add_u32_e32 v152, s18, v190
	v_add_u32_e32 v161, s18, v191
	global_load_lds_dwordx4 v[162:163], off
	v_add_u32_e32 v188, v152, v197
	v_add_u32_e32 v189, v161, v197
	ds_read_b128 v[162:165], v188
	ds_read_b128 v[166:169], v188 offset:2048
	ds_read_b128 v[220:223], v189 offset:16384
	ds_read_b128 v[224:227], v189 offset:18432
	ds_read_b128 v[228:231], v189 offset:20480
	ds_read_b128 v[232:235], v189 offset:22528
	s_waitcnt lgkmcnt(0)
	v_mfma_f32_32x32x16_bf16 v[112:127], v[162:165], v[220:223], v[112:127]
	v_add_u32_e32 v152, v152, v205
	v_add_u32_e32 v161, v161, v205
	v_lshl_add_u64 v[136:137], v[136:137], 0, s[24:25]
	s_add_u32 s12, s12, 0x80
	s_addc_u32 s13, s13, 0
	s_add_i32 s9, s9, 0x10000
	s_cmpk_lg_i32 s12, 0x800
	v_mfma_f32_32x32x16_bf16 v[96:111], v[162:165], v[224:227], v[96:111]
	v_mfma_f32_32x32x16_bf16 v[48:63], v[162:165], v[228:231], v[48:63]
	v_mfma_f32_32x32x16_bf16 v[32:47], v[162:165], v[232:235], v[32:47]
	v_mfma_f32_32x32x16_bf16 v[80:95], v[166:169], v[220:223], v[80:95]
	v_mfma_f32_32x32x16_bf16 v[64:79], v[166:169], v[224:227], v[64:79]
	v_mfma_f32_32x32x16_bf16 v[16:31], v[166:169], v[228:231], v[16:31]
	v_mfma_f32_32x32x16_bf16 v[0:15], v[166:169], v[232:235], v[0:15]
	ds_read_b128 v[162:165], v152
	ds_read_b128 v[166:169], v152 offset:2048
	ds_read_b128 v[220:223], v161 offset:16384
	ds_read_b128 v[224:227], v161 offset:18432
	ds_read_b128 v[228:231], v161 offset:20480
	ds_read_b128 v[232:235], v161 offset:22528
	s_waitcnt vmcnt(8) lgkmcnt(0)
	s_barrier
	s_waitcnt lgkmcnt(0)
	v_mfma_f32_32x32x16_bf16 v[112:127], v[162:165], v[220:223], v[112:127]
	v_mfma_f32_32x32x16_bf16 v[96:111], v[162:165], v[224:227], v[96:111]
	v_mfma_f32_32x32x16_bf16 v[48:63], v[162:165], v[228:231], v[48:63]
	v_mfma_f32_32x32x16_bf16 v[32:47], v[162:165], v[232:235], v[32:47]
	v_add_u32_e32 v162, s11, v192
	v_add_u32_e32 v163, v162, v193
	s_nop 0
	v_readfirstlane_b32 s11, v163
	s_mov_b32 m0, s11
	s_nop 0
	global_load_lds_dwordx4 v[136:137], off
	v_lshl_add_u64 v[136:137], v[138:139], 0, s[24:25]
	v_add_u32_e32 v138, v162, v194
	v_mfma_f32_32x32x16_bf16 v[80:95], v[166:169], v[220:223], v[80:95]
	v_readfirstlane_b32 s11, v138
	v_add_u32_e32 v138, v162, v195
	s_mov_b32 m0, s11
	v_readfirstlane_b32 s11, v138
	v_add_u32_e32 v138, v162, v196
	global_load_lds_dwordx4 v[136:137], off
	v_lshl_add_u64 v[136:137], v[142:143], 0, s[24:25]
	s_mov_b32 m0, s11
	v_readfirstlane_b32 s11, v138
	global_load_lds_dwordx4 v[136:137], off
	v_lshl_add_u64 v[136:137], v[140:141], 0, s[24:25]
	s_mov_b32 m0, s11
	v_mfma_f32_32x32x16_bf16 v[64:79], v[166:169], v[224:227], v[64:79]
	global_load_lds_dwordx4 v[136:137], off
	v_mfma_f32_32x32x16_bf16 v[16:31], v[166:169], v[228:231], v[16:31]
	v_mfma_f32_32x32x16_bf16 v[0:15], v[166:169], v[232:235], v[0:15]
	ds_read_b128 v[136:139], v188 offset:32768
	ds_read_b128 v[140:143], v188 offset:34816
	ds_read_b128 v[162:165], v189 offset:49152
	ds_read_b128 v[166:169], v189 offset:51200
	ds_read_b128 v[220:223], v189 offset:53248
	ds_read_b128 v[224:227], v189 offset:55296
	s_waitcnt lgkmcnt(0)
	v_mfma_f32_32x32x16_bf16 v[112:127], v[136:139], v[162:165], v[112:127]
	v_mfma_f32_32x32x16_bf16 v[96:111], v[136:139], v[166:169], v[96:111]
	v_mfma_f32_32x32x16_bf16 v[48:63], v[136:139], v[220:223], v[48:63]
	v_mfma_f32_32x32x16_bf16 v[32:47], v[136:139], v[224:227], v[32:47]
	v_mfma_f32_32x32x16_bf16 v[80:95], v[140:143], v[162:165], v[80:95]
	v_mfma_f32_32x32x16_bf16 v[64:79], v[140:143], v[166:169], v[64:79]
	v_mfma_f32_32x32x16_bf16 v[16:31], v[140:143], v[220:223], v[16:31]
	v_mfma_f32_32x32x16_bf16 v[0:15], v[140:143], v[224:227], v[0:15]
	ds_read_b128 v[136:139], v152 offset:32768
	ds_read_b128 v[140:143], v152 offset:34816
	ds_read_b128 v[162:165], v161 offset:49152
	ds_read_b128 v[166:169], v161 offset:51200
	ds_read_b128 v[220:223], v161 offset:53248
	ds_read_b128 v[224:227], v161 offset:55296
	s_waitcnt lgkmcnt(0)
	v_mfma_f32_32x32x16_bf16 v[112:127], v[136:139], v[162:165], v[112:127]
	v_mfma_f32_32x32x16_bf16 v[96:111], v[136:139], v[166:169], v[96:111]
	v_mfma_f32_32x32x16_bf16 v[48:63], v[136:139], v[220:223], v[48:63]
	v_mfma_f32_32x32x16_bf16 v[32:47], v[136:139], v[224:227], v[32:47]
	v_mfma_f32_32x32x16_bf16 v[80:95], v[140:143], v[162:165], v[80:95]
	v_mfma_f32_32x32x16_bf16 v[64:79], v[140:143], v[166:169], v[64:79]
	v_mfma_f32_32x32x16_bf16 v[16:31], v[140:143], v[220:223], v[16:31]
	v_mfma_f32_32x32x16_bf16 v[0:15], v[140:143], v[224:227], v[0:15]
	s_cbranch_scc1 .LBB0_867
; DI int crow(int i, int h) { return (i & 3) + 8 * (i >> 2) + 4 * h; }
; DI void stage_block(const f32x16& a0, const f32x16& a1, float* sE, int r, int h) {
;   _Pragma("unroll") for (int i = 0; i < 16; ++i) {
;     sE[crow(i, h) * EST + r] = a0[i];
;     sE[crow(i, h) * EST + 32 + r] = a1[i];
;   }
; }
; DI void p4_tile(const Params& P, int l, int t, char* smem) {
;     ...
;       stage_block(acc[mi][2 * seg], acc[mi][2 * seg + 1], sE, r, h);
;       _Pragma("unroll") for (int ps = 0; ps < 4; ++ps) {
;         const int rr = ps * 8 + (lane >> 3);
;         const size_t off = (size_t)(m0 + wm * 64 + mi * 32 + rr) * 2048 + gc;
;         float v[8]; read8(sE + rr * EST + ch * 8, v);
;         float g[8]; unpack8(*(const u32x4*)(P.ma + off), g);
;         _Pragma("unroll") for (int j = 0; j < 8; ++j) v[j] *= g[j];
;         *(u32x4*)(P.merged + off) = pack8u(v);
	s_movk_i32 s9, 0x2200
	v_mul_lo_u32 v128, v159, s9
	v_mul_u32_u24_e32 v130, 0x110, v157
	v_add_u32_e32 v128, 0, v128
	v_lshlrev_b32_e32 v130, 2, v130
	v_lshlrev_b32_e32 v131, 2, v155
	v_lshlrev_b32_e32 v129, 3, v156
	v_add3_u32 v188, v128, v130, v131
	v_lshrrev_b32_e32 v136, 3, v154
	v_add_u32_e32 v137, s8, v158
	s_waitcnt vmcnt(0)
	s_waitcnt vmcnt(0)
	s_barrier
	v_and_b32_e32 v129, 56, v129
	v_add3_u32 v189, v128, v131, v130
	ds_write_b32 v188, v112
	ds_write_b32 v189, v96 offset:128
	ds_write_b32 v188, v113 offset:272
	ds_write_b32 v189, v97 offset:400
	ds_write_b32 v188, v114 offset:544
	ds_write_b32 v189, v98 offset:672
	ds_write_b32 v188, v115 offset:816
	ds_write_b32 v189, v99 offset:944
	ds_write_b32 v188, v116 offset:2176
	ds_write_b32 v189, v100 offset:2304
	ds_write_b32 v188, v117 offset:2448
	ds_write_b32 v189, v101 offset:2576
	ds_write_b32 v188, v118 offset:2720
	ds_write_b32 v189, v102 offset:2848
	ds_write_b32 v188, v119 offset:2992
	ds_write_b32 v189, v103 offset:3120
	ds_write_b32 v188, v120 offset:4352
	ds_write_b32 v189, v104 offset:4480
	ds_write_b32 v188, v121 offset:4624
	ds_write_b32 v189, v105 offset:4752
	ds_write_b32 v188, v122 offset:4896
	ds_write_b32 v189, v106 offset:5024
	ds_write_b32 v188, v123 offset:5168
	ds_write_b32 v189, v107 offset:5296
	ds_write_b32 v188, v124 offset:6528
	ds_write_b32 v189, v108 offset:6656
	ds_write_b32 v188, v125 offset:6800
	ds_write_b32 v189, v109 offset:6928
	ds_write_b32 v188, v126 offset:7072
	ds_write_b32 v189, v110 offset:7200
	ds_write_b32 v188, v127 offset:7344
	ds_write_b32 v189, v111 offset:7472
	v_or_b32_e32 v96, v137, v136
	v_or3_b32 v142, v129, s10, v160
	v_ashrrev_i32_e32 v97, 31, v96
	v_ashrrev_i32_e32 v143, 31, v142
	v_lshlrev_b64 v[96:97], 11, v[96:97]
	v_lshl_add_u64 v[168:169], v[96:97], 0, v[142:143]
	v_readlane_b32 s80, v250, 10
	v_lshlrev_b64 v[102:103], 1, v[168:169]
	v_readlane_b32 s82, v250, 12
	v_readlane_b32 s83, v250, 13
	v_lshl_add_u32 v206, v129, 2, v128
	s_movk_i32 s8, 0x110
	v_lshl_add_u64 v[96:97], s[82:83], 0, v[102:103]
	global_load_dwordx4 v[98:101], v[96:97], off
	v_mad_u32_u24 v104, v136, s8, v206
	ds_read_b128 v[106:109], v104
	ds_read_b128 v[110:113], v104 offset:16
	v_lshl_add_u64 v[128:129], s[60:61], 0, v[102:103]
	v_or_b32_e32 v105, 8, v136
	v_mul_u32_u24_e32 v207, 0x110, v136
	s_lshl_b64 s[4:5], s[4:5], 1
	s_add_u32 s4, s58, s4
	s_addc_u32 s5, s59, s5
	v_lshlrev_b32_e32 v152, 1, v180
	s_add_u32 s6, s46, s6
	s_addc_u32 s7, s47, s7
	v_lshl_add_u64 v[170:171], s[58:59], 0, v[170:171]
	v_lshl_add_u64 v[172:173], s[58:59], 0, v[172:173]
	v_lshl_add_u64 v[174:175], s[2:3], 0, v[174:175]
	v_lshl_add_u64 v[176:177], s[2:3], 0, v[176:177]
	v_readlane_b32 s81, v250, 11
	v_readlane_b32 s84, v250, 14
	v_readlane_b32 s85, v250, 15
	v_readlane_b32 s86, v250, 16
	v_readlane_b32 s87, v250, 17
	v_readlane_b32 s88, v250, 18
	v_readlane_b32 s89, v250, 19
	v_readlane_b32 s90, v250, 20
	v_readlane_b32 s91, v250, 21
	v_readlane_b32 s92, v250, 22
	v_readlane_b32 s93, v250, 23
	v_readlane_b32 s94, v250, 24
	v_readlane_b32 s95, v250, 25
	s_waitcnt vmcnt(0)
	v_lshlrev_b32_e32 v114, 16, v98
	v_and_b32_e32 v115, 0xffff0000, v98
	v_lshlrev_b32_e32 v98, 16, v99
	v_and_b32_e32 v99, 0xffff0000, v99
	s_waitcnt lgkmcnt(1)
	v_pk_mul_f32 v[108:109], v[108:109], v[98:99]
	v_lshlrev_b32_e32 v98, 16, v100
	v_and_b32_e32 v99, 0xffff0000, v100
	s_waitcnt lgkmcnt(0)
	v_pk_mul_f32 v[110:111], v[110:111], v[98:99]
	v_lshlrev_b32_e32 v98, 16, v101
	v_and_b32_e32 v99, 0xffff0000, v101
	v_pk_mul_f32 v[106:107], v[106:107], v[114:115]
	v_pk_mul_f32 v[112:113], v[112:113], v[98:99]
	v_cvt_pk_bf16_f32 v98, v106, v107
	v_cvt_pk_bf16_f32 v99, v108, v109
	v_cvt_pk_bf16_f32 v100, v110, v111
	v_cvt_pk_bf16_f32 v101, v112, v113
	global_store_dwordx4 v[128:129], v[98:101], off
	ds_read_b128 v[106:109], v104 offset:2176
	s_nop 0
	v_or_b32_e32 v98, v105, v137
	v_ashrrev_i32_e32 v99, 31, v98
	v_lshlrev_b64 v[98:99], 11, v[98:99]
	v_lshl_add_u64 v[166:167], v[98:99], 0, v[142:143]
	v_lshlrev_b64 v[110:111], 1, v[166:167]
	v_lshl_add_u64 v[98:99], s[82:83], 0, v[110:111]
	global_load_dwordx4 v[100:103], v[98:99], off
	v_lshl_add_u64 v[130:131], s[60:61], 0, v[110:111]
	s_waitcnt vmcnt(0)
	v_lshlrev_b32_e32 v112, 16, v100
	v_and_b32_e32 v113, 0xffff0000, v100
	v_lshlrev_b32_e32 v100, 16, v101
	v_and_b32_e32 v101, 0xffff0000, v101
	s_waitcnt lgkmcnt(0)
	v_pk_mul_f32 v[112:113], v[106:107], v[112:113]
	v_pk_mul_f32 v[114:115], v[108:109], v[100:101]
	ds_read_b128 v[106:109], v104 offset:2192
	v_lshlrev_b32_e32 v100, 16, v102
	v_and_b32_e32 v101, 0xffff0000, v102
	s_waitcnt lgkmcnt(0)
	v_pk_mul_f32 v[106:107], v[106:107], v[100:101]
	v_lshlrev_b32_e32 v100, 16, v103
	v_and_b32_e32 v101, 0xffff0000, v103
	v_pk_mul_f32 v[108:109], v[108:109], v[100:101]
	v_cvt_pk_bf16_f32 v100, v112, v113
	v_cvt_pk_bf16_f32 v101, v114, v115
	v_cvt_pk_bf16_f32 v102, v106, v107
	v_cvt_pk_bf16_f32 v103, v108, v109
	v_or_b32_e32 v106, 16, v136
	global_store_dwordx4 v[130:131], v[100:103], off
	ds_read_b128 v[112:115], v104 offset:4352
	v_or_b32_e32 v107, 24, v136
	v_or_b32_e32 v100, v106, v137
	v_ashrrev_i32_e32 v101, 31, v100
	v_lshlrev_b64 v[100:101], 11, v[100:101]
	v_lshl_add_u64 v[164:165], v[100:101], 0, v[142:143]
	v_lshlrev_b64 v[102:103], 1, v[164:165]
	v_lshl_add_u64 v[100:101], s[82:83], 0, v[102:103]
	global_load_dwordx4 v[108:111], v[100:101], off
	v_lshl_add_u64 v[132:133], s[60:61], 0, v[102:103]
	v_or_b32_e32 v102, v107, v137
	v_ashrrev_i32_e32 v103, 31, v102
	v_lshlrev_b64 v[102:103], 11, v[102:103]
	v_lshl_add_u64 v[162:163], v[102:103], 0, v[142:143]
	s_waitcnt vmcnt(0)
; DI int crow(int i, int h) { return (i & 3) + 8 * (i >> 2) + 4 * h; }
; DI void stage_block(const f32x16& a0, const f32x16& a1, float* sE, int r, int h) {
;   _Pragma("unroll") for (int i = 0; i < 16; ++i) {
;     sE[crow(i, h) * EST + r] = a0[i];
;     sE[crow(i, h) * EST + 32 + r] = a1[i];
;   }
; }
; DI void p4_tile(const Params& P, int l, int t, char* smem) {
;     ...
;       stage_block(acc[mi][2 * seg], acc[mi][2 * seg + 1], sE, r, h);
;       _Pragma("unroll") for (int ps = 0; ps < 4; ++ps) {
;         const int rr = ps * 8 + (lane >> 3);
;         const size_t off = (size_t)(m0 + wm * 64 + mi * 32 + rr) * 2048 + gc;
;         float v[8]; read8(sE + rr * EST + ch * 8, v);
;         float g[8]; unpack8(*(const u32x4*)(P.ma + off), g);
;         _Pragma("unroll") for (int j = 0; j < 8; ++j) v[j] *= g[j];
;         *(u32x4*)(P.merged + off) = pack8u(v);
	v_lshlrev_b32_e32 v116, 16, v108
	v_and_b32_e32 v117, 0xffff0000, v108
	v_lshlrev_b32_e32 v108, 16, v109
	v_and_b32_e32 v109, 0xffff0000, v109
	s_waitcnt lgkmcnt(0)
	v_pk_mul_f32 v[116:117], v[112:113], v[116:117]
	v_pk_mul_f32 v[118:119], v[114:115], v[108:109]
	ds_read_b128 v[112:115], v104 offset:4368
	v_lshlrev_b32_e32 v108, 16, v110
	v_and_b32_e32 v109, 0xffff0000, v110
	s_waitcnt lgkmcnt(0)
	v_pk_mul_f32 v[112:113], v[112:113], v[108:109]
	v_lshlrev_b32_e32 v108, 16, v111
	v_and_b32_e32 v109, 0xffff0000, v111
	v_pk_mul_f32 v[114:115], v[114:115], v[108:109]
	v_cvt_pk_bf16_f32 v108, v116, v117
	v_cvt_pk_bf16_f32 v109, v118, v119
	v_cvt_pk_bf16_f32 v110, v112, v113
	v_cvt_pk_bf16_f32 v111, v114, v115
	v_lshlrev_b64 v[116:117], 1, v[162:163]
	global_store_dwordx4 v[132:133], v[108:111], off
	v_lshl_add_u64 v[102:103], s[82:83], 0, v[116:117]
	global_load_dwordx4 v[108:111], v[102:103], off
	ds_read_b128 v[112:115], v104 offset:6528
	v_lshl_add_u64 v[134:135], s[60:61], 0, v[116:117]
	s_waitcnt vmcnt(0)
	v_lshlrev_b32_e32 v118, 16, v108
	v_and_b32_e32 v119, 0xffff0000, v108
	v_lshlrev_b32_e32 v108, 16, v109
	v_and_b32_e32 v109, 0xffff0000, v109
	s_waitcnt lgkmcnt(0)
	v_pk_mul_f32 v[118:119], v[112:113], v[118:119]
	v_pk_mul_f32 v[120:121], v[114:115], v[108:109]
	ds_read_b128 v[112:115], v104 offset:6544
	v_lshlrev_b32_e32 v108, 16, v110
	v_and_b32_e32 v109, 0xffff0000, v110
	s_waitcnt lgkmcnt(0)
	v_pk_mul_f32 v[112:113], v[112:113], v[108:109]
	v_lshlrev_b32_e32 v108, 16, v111
	v_and_b32_e32 v109, 0xffff0000, v111
	v_pk_mul_f32 v[114:115], v[114:115], v[108:109]
	v_cvt_pk_bf16_f32 v108, v118, v119
	v_cvt_pk_bf16_f32 v109, v120, v121
	v_cvt_pk_bf16_f32 v110, v112, v113
	v_cvt_pk_bf16_f32 v111, v114, v115
	global_store_dwordx4 v[134:135], v[108:111], off
	ds_write_b32 v188, v80
	ds_write_b32 v189, v64 offset:128
	ds_write_b32 v188, v81 offset:272
	ds_write_b32 v189, v65 offset:400
	ds_write_b32 v188, v82 offset:544
	ds_write_b32 v189, v66 offset:672
	ds_write_b32 v188, v83 offset:816
	ds_write_b32 v189, v67 offset:944
	ds_write_b32 v188, v84 offset:2176
	ds_write_b32 v189, v68 offset:2304
	ds_write_b32 v188, v85 offset:2448
	ds_write_b32 v189, v69 offset:2576
	ds_write_b32 v188, v86 offset:2720
	ds_write_b32 v189, v70 offset:2848
	ds_write_b32 v188, v87 offset:2992
	ds_write_b32 v189, v71 offset:3120
	ds_write_b32 v188, v88 offset:4352
	ds_write_b32 v189, v72 offset:4480
	ds_write_b32 v188, v89 offset:4624
	ds_write_b32 v189, v73 offset:4752
	ds_write_b32 v188, v90 offset:4896
	ds_write_b32 v189, v74 offset:5024
	ds_write_b32 v188, v91 offset:5168
	ds_write_b32 v189, v75 offset:5296
	ds_write_b32 v188, v92 offset:6528
	ds_write_b32 v189, v76 offset:6656
	ds_write_b32 v188, v93 offset:6800
	ds_write_b32 v189, v77 offset:6928
	ds_write_b32 v188, v94 offset:7072
	ds_write_b32 v189, v78 offset:7200
	ds_write_b32 v188, v95 offset:7344
	ds_write_b32 v189, v79 offset:7472
	v_or_b32_e32 v70, 32, v137
	v_or_b32_e32 v64, v70, v136
	v_ashrrev_i32_e32 v65, 31, v64
	v_lshlrev_b64 v[64:65], 11, v[64:65]
	v_lshl_add_u64 v[158:159], v[64:65], 0, v[142:143]
	v_lshlrev_b64 v[80:81], 1, v[158:159]
	v_lshl_add_u64 v[64:65], s[82:83], 0, v[80:81]
	global_load_dwordx4 v[66:69], v[64:65], off
	ds_read_b128 v[72:75], v104
	ds_read_b128 v[76:79], v104 offset:16
	v_lshl_add_u64 v[136:137], s[60:61], 0, v[80:81]
	s_waitcnt vmcnt(0)
	v_lshlrev_b32_e32 v82, 16, v66
	v_and_b32_e32 v83, 0xffff0000, v66
	v_lshlrev_b32_e32 v66, 16, v67
	v_and_b32_e32 v67, 0xffff0000, v67
	s_waitcnt lgkmcnt(1)
	v_pk_mul_f32 v[74:75], v[74:75], v[66:67]
	v_lshlrev_b32_e32 v66, 16, v68
	v_and_b32_e32 v67, 0xffff0000, v68
	s_waitcnt lgkmcnt(0)
	v_pk_mul_f32 v[76:77], v[76:77], v[66:67]
	v_lshlrev_b32_e32 v66, 16, v69
	v_and_b32_e32 v67, 0xffff0000, v69
	v_pk_mul_f32 v[72:73], v[72:73], v[82:83]
	v_pk_mul_f32 v[78:79], v[78:79], v[66:67]
	v_cvt_pk_bf16_f32 v66, v72, v73
	v_cvt_pk_bf16_f32 v67, v74, v75
	v_cvt_pk_bf16_f32 v68, v76, v77
	v_cvt_pk_bf16_f32 v69, v78, v79
	global_store_dwordx4 v[136:137], v[66:69], off
	ds_read_b128 v[76:79], v104 offset:2176
	s_nop 0
	v_or_b32_e32 v66, v70, v105
	v_ashrrev_i32_e32 v67, 31, v66
	v_lshlrev_b64 v[66:67], 11, v[66:67]
	v_lshl_add_u64 v[160:161], v[66:67], 0, v[142:143]
	v_lshlrev_b64 v[68:69], 1, v[160:161]
	v_lshl_add_u64 v[66:67], s[82:83], 0, v[68:69]
	global_load_dwordx4 v[72:75], v[66:67], off
	v_lshl_add_u64 v[138:139], s[60:61], 0, v[68:69]
	v_or_b32_e32 v68, v70, v106
	v_ashrrev_i32_e32 v69, 31, v68
	v_lshlrev_b64 v[68:69], 11, v[68:69]
	v_lshl_add_u64 v[156:157], v[68:69], 0, v[142:143]
	v_or_b32_e32 v70, v70, v107
	v_ashrrev_i32_e32 v71, 31, v70
	v_lshlrev_b64 v[70:71], 11, v[70:71]
	v_lshl_add_u64 v[154:155], v[70:71], 0, v[142:143]
	s_waitcnt vmcnt(0)
	v_lshlrev_b32_e32 v80, 16, v72
	v_and_b32_e32 v81, 0xffff0000, v72
	v_lshlrev_b32_e32 v72, 16, v73
	v_and_b32_e32 v73, 0xffff0000, v73
	s_waitcnt lgkmcnt(0)
	v_pk_mul_f32 v[80:81], v[76:77], v[80:81]
	v_pk_mul_f32 v[82:83], v[78:79], v[72:73]
	ds_read_b128 v[76:79], v104 offset:2192
	v_lshlrev_b32_e32 v72, 16, v74
	v_and_b32_e32 v73, 0xffff0000, v74
	s_waitcnt lgkmcnt(0)
	v_pk_mul_f32 v[76:77], v[76:77], v[72:73]
	v_lshlrev_b32_e32 v72, 16, v75
	v_and_b32_e32 v73, 0xffff0000, v75
	v_pk_mul_f32 v[78:79], v[78:79], v[72:73]
	v_cvt_pk_bf16_f32 v72, v80, v81
	v_cvt_pk_bf16_f32 v73, v82, v83
	v_cvt_pk_bf16_f32 v74, v76, v77
	v_cvt_pk_bf16_f32 v75, v78, v79
	v_lshlrev_b64 v[80:81], 1, v[156:157]
	global_store_dwordx4 v[138:139], v[72:75], off
	v_lshl_add_u64 v[68:69], s[82:83], 0, v[80:81]
	global_load_dwordx4 v[72:75], v[68:69], off
	ds_read_b128 v[76:79], v104 offset:4352
	v_lshl_add_u64 v[140:141], s[60:61], 0, v[80:81]
	v_lshlrev_b64 v[80:81], 1, v[154:155]
	v_lshl_add_u64 v[70:71], s[82:83], 0, v[80:81]
	v_lshl_add_u64 v[142:143], s[60:61], 0, v[80:81]
	s_waitcnt vmcnt(0)
; DI void p4_tile(const Params& P, int l, int t, char* smem) {
;     ...
;   _Pragma("unroll") for (int seg = 0; seg < 2; ++seg) {
;     const int gc = n0 + wn * 128 + seg * 64 + ch * 8;
;     _Pragma("unroll") for (int mi = 0; mi < 2; ++mi) {
;       stage_block(acc[mi][2 * seg], acc[mi][2 * seg + 1], sE, r, h);
;       _Pragma("unroll") for (int ps = 0; ps < 4; ++ps) {
;         const int rr = ps * 8 + (lane >> 3);
;         const size_t off = (size_t)(m0 + wm * 64 + mi * 32 + rr) * 2048 + gc;
;         float v[8]; read8(sE + rr * EST + ch * 8, v);
;         float g[8]; unpack8(*(const u32x4*)(P.ma + off), g);
;         _Pragma("unroll") for (int j = 0; j < 8; ++j) v[j] *= g[j];
;         *(u32x4*)(P.merged + off) = pack8u(v);
	v_lshlrev_b32_e32 v82, 16, v72
	v_and_b32_e32 v83, 0xffff0000, v72
	v_lshlrev_b32_e32 v72, 16, v73
	v_and_b32_e32 v73, 0xffff0000, v73
	s_waitcnt lgkmcnt(0)
	v_pk_mul_f32 v[82:83], v[76:77], v[82:83]
	v_pk_mul_f32 v[84:85], v[78:79], v[72:73]
	ds_read_b128 v[76:79], v104 offset:4368
	v_lshlrev_b32_e32 v72, 16, v74
	v_and_b32_e32 v73, 0xffff0000, v74
	s_waitcnt lgkmcnt(0)
	v_pk_mul_f32 v[76:77], v[76:77], v[72:73]
	v_lshlrev_b32_e32 v72, 16, v75
	v_and_b32_e32 v73, 0xffff0000, v75
	v_pk_mul_f32 v[78:79], v[78:79], v[72:73]
	v_cvt_pk_bf16_f32 v72, v82, v83
	v_cvt_pk_bf16_f32 v73, v84, v85
	v_cvt_pk_bf16_f32 v74, v76, v77
	v_cvt_pk_bf16_f32 v75, v78, v79
	global_store_dwordx4 v[140:141], v[72:75], off
	global_load_dwordx4 v[72:75], v[70:71], off
	ds_read_b128 v[76:79], v104 offset:6528
	s_waitcnt vmcnt(0)
	v_lshlrev_b32_e32 v82, 16, v72
	v_and_b32_e32 v83, 0xffff0000, v72
	v_lshlrev_b32_e32 v72, 16, v73
	v_and_b32_e32 v73, 0xffff0000, v73
	s_waitcnt lgkmcnt(0)
	v_pk_mul_f32 v[82:83], v[76:77], v[82:83]
	v_pk_mul_f32 v[84:85], v[78:79], v[72:73]
	ds_read_b128 v[76:79], v104 offset:6544
	v_lshlrev_b32_e32 v72, 16, v74
	v_and_b32_e32 v73, 0xffff0000, v74
	s_waitcnt lgkmcnt(0)
	v_pk_mul_f32 v[76:77], v[76:77], v[72:73]
	v_lshlrev_b32_e32 v72, 16, v75
	v_and_b32_e32 v73, 0xffff0000, v75
	v_pk_mul_f32 v[78:79], v[78:79], v[72:73]
	v_cvt_pk_bf16_f32 v72, v82, v83
	v_cvt_pk_bf16_f32 v73, v84, v85
	v_cvt_pk_bf16_f32 v74, v76, v77
	v_cvt_pk_bf16_f32 v75, v78, v79
	global_store_dwordx4 v[142:143], v[72:75], off
	ds_write_b32 v188, v48
	ds_write_b32 v189, v32 offset:128
	ds_write_b32 v188, v49 offset:272
	ds_write_b32 v189, v33 offset:400
	ds_write_b32 v188, v50 offset:544
	ds_write_b32 v189, v34 offset:672
	ds_write_b32 v188, v51 offset:816
	ds_write_b32 v189, v35 offset:944
	ds_write_b32 v188, v52 offset:2176
	ds_write_b32 v189, v36 offset:2304
	ds_write_b32 v188, v53 offset:2448
	ds_write_b32 v189, v37 offset:2576
	ds_write_b32 v188, v54 offset:2720
	ds_write_b32 v189, v38 offset:2848
	ds_write_b32 v188, v55 offset:2992
	ds_write_b32 v189, v39 offset:3120
	ds_write_b32 v188, v56 offset:4352
	ds_write_b32 v189, v40 offset:4480
	ds_write_b32 v188, v57 offset:4624
	ds_write_b32 v189, v41 offset:4752
	ds_write_b32 v188, v58 offset:4896
	ds_write_b32 v189, v42 offset:5024
	ds_write_b32 v188, v59 offset:5168
	ds_write_b32 v189, v43 offset:5296
	ds_write_b32 v188, v60 offset:6528
	ds_write_b32 v189, v44 offset:6656
	ds_write_b32 v188, v61 offset:6800
	ds_write_b32 v189, v45 offset:6928
	ds_write_b32 v188, v62 offset:7072
	ds_write_b32 v189, v46 offset:7200
	ds_write_b32 v188, v63 offset:7344
	ds_write_b32 v189, v47 offset:7472
	global_load_dwordx4 v[220:223], v[96:97], off offset:128
	global_load_dwordx4 v[224:227], v[98:99], off offset:128
	global_load_dwordx4 v[228:231], v[100:101], off offset:128
	global_load_dwordx4 v[232:235], v[102:103], off offset:128
	global_load_dwordx4 v[236:239], v[64:65], off offset:128
	global_load_dwordx4 v[240:243], v[66:67], off offset:128
	ds_read_b128 v[36:39], v104
	ds_read_b128 v[40:43], v104 offset:16
	s_waitcnt vmcnt(5)
	v_lshlrev_b32_e32 v44, 16, v220
	v_and_b32_e32 v45, 0xffff0000, v220
	v_lshlrev_b32_e32 v32, 16, v221
	v_and_b32_e32 v33, 0xffff0000, v221
	s_waitcnt lgkmcnt(1)
	v_pk_mul_f32 v[38:39], v[38:39], v[32:33]
	v_lshlrev_b32_e32 v32, 16, v222
	v_and_b32_e32 v33, 0xffff0000, v222
	s_waitcnt lgkmcnt(0)
	v_pk_mul_f32 v[40:41], v[40:41], v[32:33]
	v_lshlrev_b32_e32 v32, 16, v223
	v_and_b32_e32 v33, 0xffff0000, v223
	v_pk_mul_f32 v[36:37], v[36:37], v[44:45]
	v_pk_mul_f32 v[42:43], v[42:43], v[32:33]
	v_cvt_pk_bf16_f32 v32, v36, v37
	v_cvt_pk_bf16_f32 v33, v38, v39
	v_cvt_pk_bf16_f32 v34, v40, v41
	v_cvt_pk_bf16_f32 v35, v42, v43
	global_store_dwordx4 v[128:129], v[32:35], off offset:128
	ds_read_b128 v[36:39], v104 offset:2176
	s_waitcnt vmcnt(5)
	v_lshlrev_b32_e32 v40, 16, v224
	v_and_b32_e32 v41, 0xffff0000, v224
	v_lshlrev_b32_e32 v32, 16, v225
	v_and_b32_e32 v33, 0xffff0000, v225
	s_waitcnt lgkmcnt(0)
	v_pk_mul_f32 v[40:41], v[36:37], v[40:41]
	v_pk_mul_f32 v[42:43], v[38:39], v[32:33]
	ds_read_b128 v[36:39], v104 offset:2192
	v_lshlrev_b32_e32 v32, 16, v226
	v_and_b32_e32 v33, 0xffff0000, v226
	s_waitcnt lgkmcnt(0)
	v_pk_mul_f32 v[36:37], v[36:37], v[32:33]
	v_lshlrev_b32_e32 v32, 16, v227
	v_and_b32_e32 v33, 0xffff0000, v227
	v_pk_mul_f32 v[38:39], v[38:39], v[32:33]
	v_cvt_pk_bf16_f32 v32, v40, v41
	v_cvt_pk_bf16_f32 v33, v42, v43
	v_cvt_pk_bf16_f32 v34, v36, v37
	v_cvt_pk_bf16_f32 v35, v38, v39
	global_store_dwordx4 v[130:131], v[32:35], off offset:128
	global_load_dwordx4 v[220:223], v[68:69], off offset:128
	ds_read_b128 v[36:39], v104 offset:4352
	s_waitcnt vmcnt(6)
	v_lshlrev_b32_e32 v40, 16, v228
	v_and_b32_e32 v41, 0xffff0000, v228
	v_lshlrev_b32_e32 v32, 16, v229
	v_and_b32_e32 v33, 0xffff0000, v229
	s_waitcnt lgkmcnt(0)
	v_pk_mul_f32 v[40:41], v[36:37], v[40:41]
	v_pk_mul_f32 v[42:43], v[38:39], v[32:33]
	ds_read_b128 v[36:39], v104 offset:4368
	v_lshlrev_b32_e32 v32, 16, v230
	v_and_b32_e32 v33, 0xffff0000, v230
	s_waitcnt lgkmcnt(0)
	v_pk_mul_f32 v[36:37], v[36:37], v[32:33]
	v_lshlrev_b32_e32 v32, 16, v231
	v_and_b32_e32 v33, 0xffff0000, v231
	v_pk_mul_f32 v[38:39], v[38:39], v[32:33]
	v_cvt_pk_bf16_f32 v32, v40, v41
	v_cvt_pk_bf16_f32 v33, v42, v43
	v_cvt_pk_bf16_f32 v34, v36, v37
	v_cvt_pk_bf16_f32 v35, v38, v39
	global_store_dwordx4 v[132:133], v[32:35], off offset:128
	global_load_dwordx4 v[224:227], v[70:71], off offset:128
	ds_read_b128 v[36:39], v104 offset:6528
	s_waitcnt vmcnt(7)
	v_lshlrev_b32_e32 v40, 16, v232
	v_and_b32_e32 v41, 0xffff0000, v232
	v_lshlrev_b32_e32 v32, 16, v233
	v_and_b32_e32 v33, 0xffff0000, v233
	s_waitcnt lgkmcnt(0)
; DI void p4_tile(const Params& P, int l, int t, char* smem) {
;     ...
;   _Pragma("unroll") for (int seg = 0; seg < 2; ++seg) {
;     const int gc = n0 + wn * 128 + seg * 64 + ch * 8;
;     _Pragma("unroll") for (int mi = 0; mi < 2; ++mi) {
;       stage_block(acc[mi][2 * seg], acc[mi][2 * seg + 1], sE, r, h);
;       _Pragma("unroll") for (int ps = 0; ps < 4; ++ps) {
;         const int rr = ps * 8 + (lane >> 3);
;         const size_t off = (size_t)(m0 + wm * 64 + mi * 32 + rr) * 2048 + gc;
;         float v[8]; read8(sE + rr * EST + ch * 8, v);
;         float g[8]; unpack8(*(const u32x4*)(P.ma + off), g);
;         _Pragma("unroll") for (int j = 0; j < 8; ++j) v[j] *= g[j];
;         *(u32x4*)(P.merged + off) = pack8u(v);
	v_pk_mul_f32 v[40:41], v[36:37], v[40:41]
	v_pk_mul_f32 v[42:43], v[38:39], v[32:33]
	ds_read_b128 v[36:39], v104 offset:6544
	v_lshlrev_b32_e32 v32, 16, v234
	v_and_b32_e32 v33, 0xffff0000, v234
	s_waitcnt lgkmcnt(0)
	v_pk_mul_f32 v[36:37], v[36:37], v[32:33]
	v_lshlrev_b32_e32 v32, 16, v235
	v_and_b32_e32 v33, 0xffff0000, v235
	v_pk_mul_f32 v[38:39], v[38:39], v[32:33]
	v_cvt_pk_bf16_f32 v32, v40, v41
	v_cvt_pk_bf16_f32 v33, v42, v43
	v_cvt_pk_bf16_f32 v34, v36, v37
	v_cvt_pk_bf16_f32 v35, v38, v39
	global_store_dwordx4 v[134:135], v[32:35], off offset:128
	ds_write_b32 v188, v16
	ds_write_b32 v189, v0 offset:128
	ds_write_b32 v188, v17 offset:272
	ds_write_b32 v189, v1 offset:400
	ds_write_b32 v188, v18 offset:544
	ds_write_b32 v189, v2 offset:672
	ds_write_b32 v188, v19 offset:816
	ds_write_b32 v189, v3 offset:944
	ds_write_b32 v188, v20 offset:2176
	ds_write_b32 v189, v4 offset:2304
	ds_write_b32 v188, v21 offset:2448
	ds_write_b32 v189, v5 offset:2576
	ds_write_b32 v188, v22 offset:2720
	ds_write_b32 v189, v6 offset:2848
	ds_write_b32 v188, v23 offset:2992
	ds_write_b32 v189, v7 offset:3120
	ds_write_b32 v188, v24 offset:4352
	ds_write_b32 v189, v8 offset:4480
	ds_write_b32 v188, v25 offset:4624
	ds_write_b32 v189, v9 offset:4752
	ds_write_b32 v188, v26 offset:4896
	ds_write_b32 v189, v10 offset:5024
	ds_write_b32 v188, v27 offset:5168
	ds_write_b32 v189, v11 offset:5296
	ds_write_b32 v188, v28 offset:6528
	ds_write_b32 v189, v12 offset:6656
	ds_write_b32 v188, v29 offset:6800
	ds_write_b32 v189, v13 offset:6928
	ds_write_b32 v188, v30 offset:7072
	ds_write_b32 v189, v14 offset:7200
	ds_write_b32 v188, v31 offset:7344
	ds_write_b32 v189, v15 offset:7472
	ds_read_b128 v[4:7], v104
	ds_read_b128 v[8:11], v104 offset:16
	s_waitcnt vmcnt(7)
	v_lshlrev_b32_e32 v12, 16, v236
	v_and_b32_e32 v13, 0xffff0000, v236
	v_lshlrev_b32_e32 v0, 16, v237
	v_and_b32_e32 v1, 0xffff0000, v237
	s_waitcnt lgkmcnt(1)
	v_pk_mul_f32 v[6:7], v[6:7], v[0:1]
	v_lshlrev_b32_e32 v0, 16, v238
	v_and_b32_e32 v1, 0xffff0000, v238
	s_waitcnt lgkmcnt(0)
	v_pk_mul_f32 v[8:9], v[8:9], v[0:1]
	v_lshlrev_b32_e32 v0, 16, v239
	v_and_b32_e32 v1, 0xffff0000, v239
	v_pk_mul_f32 v[4:5], v[4:5], v[12:13]
	v_pk_mul_f32 v[10:11], v[10:11], v[0:1]
	v_cvt_pk_bf16_f32 v0, v4, v5
	v_cvt_pk_bf16_f32 v1, v6, v7
	v_cvt_pk_bf16_f32 v2, v8, v9
	v_cvt_pk_bf16_f32 v3, v10, v11
	global_store_dwordx4 v[136:137], v[0:3], off offset:128
	ds_read_b128 v[4:7], v104 offset:2176
	s_waitcnt vmcnt(7)
	v_lshlrev_b32_e32 v8, 16, v240
	v_and_b32_e32 v9, 0xffff0000, v240
	v_lshlrev_b32_e32 v0, 16, v241
	v_and_b32_e32 v1, 0xffff0000, v241
	s_waitcnt lgkmcnt(0)
	v_pk_mul_f32 v[8:9], v[4:5], v[8:9]
	v_pk_mul_f32 v[10:11], v[6:7], v[0:1]
	ds_read_b128 v[4:7], v104 offset:2192
	v_lshlrev_b32_e32 v0, 16, v242
	v_and_b32_e32 v1, 0xffff0000, v242
	s_waitcnt lgkmcnt(0)
	v_pk_mul_f32 v[4:5], v[4:5], v[0:1]
	v_lshlrev_b32_e32 v0, 16, v243
	v_and_b32_e32 v1, 0xffff0000, v243
	v_pk_mul_f32 v[6:7], v[6:7], v[0:1]
	v_cvt_pk_bf16_f32 v0, v8, v9
	v_cvt_pk_bf16_f32 v1, v10, v11
	v_cvt_pk_bf16_f32 v2, v4, v5
	v_cvt_pk_bf16_f32 v3, v6, v7
	global_store_dwordx4 v[138:139], v[0:3], off offset:128
	ds_read_b128 v[4:7], v104 offset:4352
	s_waitcnt vmcnt(5)
	v_lshlrev_b32_e32 v8, 16, v220
	v_and_b32_e32 v9, 0xffff0000, v220
	v_lshlrev_b32_e32 v0, 16, v221
	v_and_b32_e32 v1, 0xffff0000, v221
	s_waitcnt lgkmcnt(0)
	v_pk_mul_f32 v[8:9], v[4:5], v[8:9]
	v_pk_mul_f32 v[10:11], v[6:7], v[0:1]
	ds_read_b128 v[4:7], v104 offset:4368
	v_lshlrev_b32_e32 v0, 16, v222
	v_and_b32_e32 v1, 0xffff0000, v222
	s_waitcnt lgkmcnt(0)
	v_pk_mul_f32 v[4:5], v[4:5], v[0:1]
	v_lshlrev_b32_e32 v0, 16, v223
	v_and_b32_e32 v1, 0xffff0000, v223
	v_pk_mul_f32 v[6:7], v[6:7], v[0:1]
	v_cvt_pk_bf16_f32 v0, v8, v9
	v_cvt_pk_bf16_f32 v1, v10, v11
	v_cvt_pk_bf16_f32 v2, v4, v5
	v_cvt_pk_bf16_f32 v3, v6, v7
	global_store_dwordx4 v[140:141], v[0:3], off offset:128
	ds_read_b128 v[4:7], v104 offset:6528
	s_waitcnt vmcnt(4)
	v_lshlrev_b32_e32 v8, 16, v224
	v_and_b32_e32 v9, 0xffff0000, v224
	v_lshlrev_b32_e32 v0, 16, v225
	v_and_b32_e32 v1, 0xffff0000, v225
	s_waitcnt lgkmcnt(0)
	v_pk_mul_f32 v[8:9], v[4:5], v[8:9]
	v_pk_mul_f32 v[10:11], v[6:7], v[0:1]
	ds_read_b128 v[4:7], v104 offset:6544
	v_lshlrev_b32_e32 v0, 16, v226
	v_and_b32_e32 v1, 0xffff0000, v226
	s_waitcnt lgkmcnt(0)
	v_pk_mul_f32 v[4:5], v[4:5], v[0:1]
	v_lshlrev_b32_e32 v0, 16, v227
	v_and_b32_e32 v1, 0xffff0000, v227
	v_pk_mul_f32 v[6:7], v[6:7], v[0:1]
	v_cvt_pk_bf16_f32 v0, v8, v9
	v_cvt_pk_bf16_f32 v1, v10, v11
	v_cvt_pk_bf16_f32 v2, v4, v5
	v_cvt_pk_bf16_f32 v3, v6, v7
	global_store_dwordx4 v[142:143], v[0:3], off offset:128
	s_barrier
; DI f32x16 zero16() { f32x16 z; _Pragma("unroll") for (int i = 0; i < 16; ++i) z[i] = 0.f; return z; }
; DI void dma_stage(const bf16_t* __restrict__ A, int lda, const bf16_t* __restrict__ B, int ldb, int k0, char* stage, int w, int lane) {
;   const int lr = lane >> 2, pos = lane & 3;
;   _Pragma("unroll") for (int i = 0; i < 4; ++i) {
;     const int idx = w + 8 * i;
;     const int row = (idx << 4) + lr;
;     const int c = pos ^ ((row >> 2) & 3);
;     const bf16_t* g = (i < 2) ? (A + (size_t)row * lda + k0 + c * 8) : (B + (size_t)(row - 256) * ldb + k0 + c * 8);
;     __builtin_amdgcn_global_load_lds((const unsigned*)g, (unsigned*)(stage + idx * 1024 + lane * 16), 16, 0, 0);
;   }
; }
; DI void gemm_mainloop(const bf16_t* __restrict__ A, int lda, const bf16_t* __restrict__ B, int ldb, int K,
;                       f32x16 (&acc)[2][4], char* smem, const int tid) {
;   const int lane = tid & 63, w = tid >> 6;
;   const int wm = w >> 1, wn = w & 1, r = lane & 31, h = lane >> 5;
;   const int swz = (r >> 2) & 3;
;   const int o0 = ((0 + h) ^ swz) << 4, o1 = ((2 + h) ^ swz) << 4;
;   const int aoff = (wm * 64 + r) * 64, boff = (256 + wn * 128 + r) * 64;
;   const int nk = K >> 5;
;   dma_stage(A, lda, B, ldb, 0, smem, w, lane);
;   dma_stage(A, lda, B, ldb, 32, smem + STG, w, lane);
;   dma_stage(A, lda, B, ldb, 64, smem + 2 * STG, w, lane);
; DI void zero_acc(f32x16 (&acc)[2][4]) {
;   _Pragma("unroll") for (int i = 0; i < 2; ++i) { _Pragma("unroll") for (int j = 0; j < 4; ++j) acc[i][j] = zero16(); }
; }
	s_nop 0
	v_lshl_add_u64 v[2:3], s[4:5], 0, v[152:153]
	v_readfirstlane_b32 s4, v218
	v_lshl_add_u64 v[4:5], v[186:187], 1, v[2:3]
	s_mov_b32 m0, s4
	v_readfirstlane_b32 s4, v217
	v_lshl_add_u64 v[0:1], s[6:7], 0, v[152:153]
	global_load_lds_dwordx4 v[4:5], off
	v_lshl_add_u64 v[2:3], v[184:185], 1, v[2:3]
	s_mov_b32 m0, s4
	v_readfirstlane_b32 s4, v216
	global_load_lds_dwordx4 v[2:3], off
	v_lshl_add_u64 v[6:7], v[182:183], 1, v[0:1]
	s_mov_b32 m0, s4
	v_readfirstlane_b32 s4, v215
	global_load_lds_dwordx4 v[6:7], off
	v_lshl_add_u64 v[0:1], v[178:179], 1, v[0:1]
	s_mov_b32 m0, s4
	v_readfirstlane_b32 s4, v214
	global_load_lds_dwordx4 v[0:1], off
	v_lshl_add_u64 v[8:9], v[4:5], 0, 64
	s_mov_b32 m0, s4
	v_readfirstlane_b32 s4, v213
	global_load_lds_dwordx4 v[8:9], off
	v_lshl_add_u64 v[8:9], v[2:3], 0, 64
	s_mov_b32 m0, s4
	v_readfirstlane_b32 s4, v212
	global_load_lds_dwordx4 v[8:9], off
	v_lshl_add_u64 v[8:9], v[6:7], 0, 64
	s_mov_b32 m0, s4
	v_readfirstlane_b32 s4, v211
	global_load_lds_dwordx4 v[8:9], off
	v_lshl_add_u64 v[8:9], v[0:1], 0, 64
	s_mov_b32 m0, s4
	s_mov_b64 s[6:7], 0x80
	v_readfirstlane_b32 s4, v210
	global_load_lds_dwordx4 v[8:9], off
	v_lshl_add_u64 v[4:5], v[4:5], 0, s[6:7]
	s_mov_b32 m0, s4
	v_readfirstlane_b32 s4, v209
	global_load_lds_dwordx4 v[4:5], off
	v_lshl_add_u64 v[2:3], v[2:3], 0, s[6:7]
	s_mov_b32 m0, s4
	v_readfirstlane_b32 s4, v208
	global_load_lds_dwordx4 v[2:3], off
	v_lshl_add_u64 v[2:3], v[6:7], 0, s[6:7]
	s_mov_b32 m0, s4
	v_readfirstlane_b32 s4, v181
	global_load_lds_dwordx4 v[2:3], off
	v_lshl_add_u64 v[0:1], v[0:1], 0, s[6:7]
	s_mov_b32 m0, s4
	s_mov_b64 s[4:5], 0
	global_load_lds_dwordx4 v[0:1], off
	v_mov_b32_e32 v0, 0
	s_mov_b32 s6, 0
	v_mov_b32_e32 v1, v0
	v_mov_b32_e32 v2, v0
	v_mov_b32_e32 v3, v0
	v_mov_b32_e32 v4, v0
	v_mov_b32_e32 v5, v0
	v_mov_b32_e32 v6, v0
	v_mov_b32_e32 v7, v0
	v_mov_b32_e32 v8, v0
	v_mov_b32_e32 v9, v0
	v_mov_b32_e32 v10, v0
	v_mov_b32_e32 v11, v0
	v_mov_b32_e32 v12, v0
	v_mov_b32_e32 v13, v0
	v_mov_b32_e32 v14, v0
	v_mov_b32_e32 v15, v0
	v_mov_b32_e32 v16, v0
	v_mov_b32_e32 v17, v0
	v_mov_b32_e32 v18, v0
	v_mov_b32_e32 v19, v0
	v_mov_b32_e32 v20, v0
	v_mov_b32_e32 v21, v0
	v_mov_b32_e32 v22, v0
	v_mov_b32_e32 v23, v0
	v_mov_b32_e32 v24, v0
	v_mov_b32_e32 v25, v0
	v_mov_b32_e32 v26, v0
	v_mov_b32_e32 v27, v0
	v_mov_b32_e32 v28, v0
	v_mov_b32_e32 v29, v0
	v_mov_b32_e32 v30, v0
	v_mov_b32_e32 v31, v0
	v_mov_b32_e32 v64, v0
	v_mov_b32_e32 v65, v0
	v_mov_b32_e32 v66, v0
	v_mov_b32_e32 v67, v0
	v_mov_b32_e32 v68, v0
	v_mov_b32_e32 v69, v0
	v_mov_b32_e32 v70, v0
	v_mov_b32_e32 v71, v0
	v_mov_b32_e32 v72, v0
	v_mov_b32_e32 v73, v0
	v_mov_b32_e32 v74, v0
	v_mov_b32_e32 v75, v0
	v_mov_b32_e32 v76, v0
	v_mov_b32_e32 v77, v0
	v_mov_b32_e32 v78, v0
	v_mov_b32_e32 v79, v0
	v_mov_b32_e32 v80, v0
	v_mov_b32_e32 v81, v0
	v_mov_b32_e32 v82, v0
	v_mov_b32_e32 v83, v0
	v_mov_b32_e32 v84, v0
	v_mov_b32_e32 v85, v0
	v_mov_b32_e32 v86, v0
	v_mov_b32_e32 v87, v0
	v_mov_b32_e32 v88, v0
	v_mov_b32_e32 v89, v0
	v_mov_b32_e32 v90, v0
	v_mov_b32_e32 v91, v0
	v_mov_b32_e32 v92, v0
	v_mov_b32_e32 v93, v0
	v_mov_b32_e32 v94, v0
	v_mov_b32_e32 v95, v0
	v_mov_b32_e32 v32, v0
	v_mov_b32_e32 v33, v0
	v_mov_b32_e32 v34, v0
	v_mov_b32_e32 v35, v0
	v_mov_b32_e32 v36, v0
	v_mov_b32_e32 v37, v0
	v_mov_b32_e32 v38, v0
	v_mov_b32_e32 v39, v0
	v_mov_b32_e32 v40, v0
	v_mov_b32_e32 v41, v0
	v_mov_b32_e32 v42, v0
	v_mov_b32_e32 v43, v0
	v_mov_b32_e32 v44, v0
	v_mov_b32_e32 v45, v0
	v_mov_b32_e32 v46, v0
	v_mov_b32_e32 v47, v0
	v_mov_b32_e32 v48, v0
	v_mov_b32_e32 v49, v0
	v_mov_b32_e32 v50, v0
	v_mov_b32_e32 v51, v0
	v_mov_b32_e32 v52, v0
	v_mov_b32_e32 v53, v0
	v_mov_b32_e32 v54, v0
	v_mov_b32_e32 v55, v0
	v_mov_b32_e32 v56, v0
	v_mov_b32_e32 v57, v0
	v_mov_b32_e32 v58, v0
	v_mov_b32_e32 v59, v0
	v_mov_b32_e32 v60, v0
	v_mov_b32_e32 v61, v0
	v_mov_b32_e32 v62, v0
	v_mov_b32_e32 v63, v0
	v_mov_b32_e32 v96, v0
	v_mov_b32_e32 v97, v0
	v_mov_b32_e32 v98, v0
	v_mov_b32_e32 v99, v0
	v_mov_b32_e32 v100, v0
	v_mov_b32_e32 v101, v0
	v_mov_b32_e32 v102, v0
	v_mov_b32_e32 v103, v0
	v_mov_b32_e32 v104, v0
	v_mov_b32_e32 v105, v0
	v_mov_b32_e32 v106, v0
	v_mov_b32_e32 v107, v0
	v_mov_b32_e32 v108, v0
	v_mov_b32_e32 v109, v0
	v_mov_b32_e32 v110, v0
	v_mov_b32_e32 v111, v0
	v_mov_b32_e32 v112, v0
	v_mov_b32_e32 v113, v0
	v_mov_b32_e32 v114, v0
	v_mov_b32_e32 v115, v0
	v_mov_b32_e32 v116, v0
	v_mov_b32_e32 v117, v0
	v_mov_b32_e32 v118, v0
	v_mov_b32_e32 v119, v0
	v_mov_b32_e32 v120, v0
	v_mov_b32_e32 v121, v0
	v_mov_b32_e32 v122, v0
	v_mov_b32_e32 v123, v0
	v_mov_b32_e32 v124, v0
	v_mov_b32_e32 v125, v0
	v_mov_b32_e32 v126, v0
	v_mov_b32_e32 v127, v0
